# selected-branch steps: chunk id, selection masks and the following chunk id all fetched before the previous step's barrier (no LDS round trip at the step top)
# baseline (speedup 1.0000x reference)
.LBB0_619:
	s_or_b64 exec, exec, s[0:1]
	v_lshlrev_b32_e32 v29, 5, v111
	v_add_u32_e32 v0, s68, v29
	v_or_b32_e32 v160, v0, v109
	v_or_b32_e32 v156, 16, v160
	v_ashrrev_i32_e32 v161, 31, v160
	v_ashrrev_i32_e32 v157, 31, v156
	v_lshlrev_b64 v[164:165], 12, v[160:161]
	v_lshlrev_b64 v[162:163], 12, v[156:157]
	v_lshl_add_u64 v[12:13], v[82:83], 0, v[164:165]
	v_lshl_add_u64 v[30:31], v[82:83], 0, v[162:163]
	s_waitcnt lgkmcnt(0)
	s_barrier
	flat_load_dwordx4 v[0:3], v[12:13]
	flat_load_dwordx4 v[4:7], v[12:13] offset:64
	flat_load_dwordx4 v[8:11], v[12:13] offset:128
	s_nop 0
	flat_load_dwordx4 v[12:15], v[12:13] offset:192
	s_nop 0
	flat_load_dwordx4 v[16:19], v[30:31]
	flat_load_dwordx4 v[20:23], v[30:31] offset:64
	flat_load_dwordx4 v[24:27], v[30:31] offset:128
	flat_load_dwordx4 v[32:35], v[30:31] offset:192
	v_readlane_b32 s0, v246, 6
	s_lshl_b32 s26, s69, 7
	s_lshl_b32 s27, s69, 20
	v_mov_b32_e32 v30, s0
	ds_read_b32 v30, v30
	s_waitcnt lgkmcnt(0)
	v_cmp_eq_u32_e32 vcc, 0, v30
	v_readfirstlane_b32 s28, v30
	s_cbranch_vccnz .LBB0_679
	v_mov_b32_e32 v52, v154
	v_mov_b32_e32 v30, v155
	v_mov_b32_e32 v31, s50
	ds_read_b32 v31, v31
	s_lshl_b32 s0, s26, 1
	s_add_u32 s12, s43, s0
	s_addc_u32 s13, s42, 0
	s_lshl_b32 s0, s27, 1
	s_add_u32 s14, s45, s0
	s_mov_b32 s0, 0x60000
	s_waitcnt lgkmcnt(0)
	v_mul_hi_i32 v37, v31, s0
	v_mul_lo_u32 v36, v31, s0
	v_lshl_add_u64 v[40:41], s[12:13], 0, v[36:37]
	v_lshlrev_b32_e32 v36, 6, v31
	v_ashrrev_i32_e32 v37, 31, v36
	s_addc_u32 s15, s44, 0
	v_lshlrev_b64 v[36:37], 1, v[36:37]
	v_lshlrev_b32_e32 v31, 3, v52
	v_lshrrev_b32_e32 v53, 4, v52
	s_movk_i32 s0, 0xc00
	v_lshl_add_u64 v[48:49], s[14:15], 0, v[36:37]
	v_and_b32_e32 v42, 0x78, v31
	v_mul_lo_u32 v36, v53, s0
	v_or_b32_e32 v166, v36, v42
	v_mov_b32_e32 v167, v28
	v_lshl_add_u64 v[36:37], v[166:167], 1, v[40:41]
	v_add_u32_e32 v54, 0x200, v52
	global_load_dwordx4 v[36:39], v[36:37], off offset:2048
	v_lshrrev_b32_e32 v55, 4, v54
	v_mul_lo_u32 v43, v55, s0
	v_and_b32_e32 v31, 56, v31
	v_lshlrev_b32_e32 v44, 10, v52
	s_movk_i32 s0, 0xe000
	v_lshlrev_b32_e32 v50, 10, v54
	v_or_b32_e32 v168, v43, v42
	v_mov_b32_e32 v169, v28
	v_and_or_b32 v170, v44, s0, v31
	v_mov_b32_e32 v171, v28
	v_and_or_b32 v172, v50, s0, v31
	v_mov_b32_e32 v173, v28
	v_lshl_add_u64 v[40:41], v[168:169], 1, v[40:41]
	v_lshl_add_u64 v[44:45], v[170:171], 1, v[48:49]
	v_lshl_add_u64 v[48:49], v[172:173], 1, v[48:49]
	global_load_dwordx4 v[40:43], v[40:41], off offset:2048
	v_lshlrev_b32_e32 v56, 4, v52
	global_load_dwordx4 v[44:47], v[44:45], off
	v_and_b32_e32 v31, 0xf0, v56
	global_load_dwordx4 v[48:51], v[48:49], off
	v_add_u32_e32 v57, s54, v31
	v_mul_lo_u32 v157, v53, s83
	v_add_u32_e32 v161, v57, v157
	v_mul_lo_u32 v189, v55, s83
	v_add_u32_e32 v190, v57, v189
	v_readfirstlane_b32 s0, v160
	s_cmp_lt_i32 s28, 1
	s_waitcnt vmcnt(0)
	ds_write_b128 v161, v[36:39]
	v_lshrrev_b32_e32 v38, 3, v52
	v_and_b32_e32 v36, 0x70, v56
	v_mul_lo_u32 v191, v38, s88
	v_lshrrev_b32_e32 v38, 3, v54
	v_add_u32_e32 v37, s79, v36
	v_mul_lo_u32 v193, v38, s88
	v_add_u32_e32 v192, v37, v191
	v_add_u32_e32 v194, v37, v193
	ds_write_b128 v190, v[40:43]
	ds_write_b128 v192, v[44:47]
	ds_write_b128 v194, v[48:51]
	s_waitcnt lgkmcnt(0)
	s_barrier
	s_cbranch_scc1 .LBB0_680
	v_or_b32_e32 v29, v29, v109
	s_add_i32 s1, 0, 0x14440
	v_lshl_add_u32 v195, v29, 4, s1
	v_and_b32_e32 v29, 15, v30
	v_and_b32_e32 v37, -16, v30
	v_ashrrev_i32_e32 v30, 4, v30
	v_lshlrev_b32_e32 v209, 2, v30
	v_lshlrev_b32_e32 v30, 3, v30
	v_add_u32_e32 v38, s54, v37
	v_mul_u32_u24_e32 v39, 0x110, v29
	v_add_u32_e32 v40, s79, v30
	v_mul_u32_u24_e32 v41, 0x90, v29
	v_add_u32_e32 v210, 0, v36
	v_add_u32_e32 v211, 0, v31
	v_add_u32_e32 v36, 0, v37
	v_add_u32_e32 v37, 0, v30
	v_mov_b32_e32 v30, v28
	v_mov_b32_e32 v31, v28
	v_mov_b32_e32 v29, v28
	v_add_u32_e32 v212, v38, v39
	v_add_u32_e32 v213, v40, v41
	v_add_u32_e32 v214, v36, v39
	v_add_u32_e32 v215, v37, v41
	v_mov_b64_e32 v[38:39], v[30:31]
	v_mov_b64_e32 v[42:43], v[30:31]
	v_mov_b64_e32 v[46:47], v[30:31]
	v_mov_b64_e32 v[50:51], v[30:31]
	v_mov_b64_e32 v[54:55], v[30:31]
	v_mov_b64_e32 v[58:59], v[30:31]
	v_mov_b64_e32 v[62:63], v[30:31]
	v_mov_b64_e32 v[66:67], v[30:31]
	v_mov_b64_e32 v[70:71], v[30:31]
	v_mov_b64_e32 v[74:75], v[30:31]
	v_mov_b64_e32 v[78:79], v[30:31]
	v_mov_b64_e32 v[82:83], v[30:31]
	v_mov_b64_e32 v[86:87], v[30:31]
	v_mov_b64_e32 v[90:91], v[30:31]
	v_mov_b64_e32 v[94:95], v[30:31]
	v_mov_b64_e32 v[98:99], v[30:31]
	s_sub_i32 s29, s0, 63
	s_mov_b32 s31, 0
	v_mov_b32_e32 v217, 0xf149f2ca
	v_mov_b32_e32 v117, 0
	v_readlane_b32 s30, v244, 7
	v_mov_b64_e32 v[36:37], v[28:29]
	v_mov_b64_e32 v[40:41], v[28:29]
	v_mov_b64_e32 v[44:45], v[28:29]
	v_mov_b64_e32 v[48:49], v[28:29]
	v_mov_b64_e32 v[52:53], v[28:29]
	v_mov_b64_e32 v[56:57], v[28:29]
	v_mov_b64_e32 v[60:61], v[28:29]
	v_mov_b64_e32 v[64:65], v[28:29]
	v_mov_b64_e32 v[68:69], v[28:29]
	v_mov_b64_e32 v[72:73], v[28:29]
	v_mov_b64_e32 v[76:77], v[28:29]
	v_mov_b64_e32 v[80:81], v[28:29]
	v_mov_b64_e32 v[84:85], v[28:29]
	v_mov_b64_e32 v[88:89], v[28:29]
	v_mov_b64_e32 v[92:93], v[28:29]
	v_mov_b64_e32 v[96:97], v[28:29]
	v_mov_b32_e32 v116, 0
	v_mov_b32_e32 v218, 0xf149f2ca
	v_mov_b32_e32 v216, 0
	v_mov_b32_e32 v29, 0
	ds_read_b32 v239, v151 offset:9728
	s_add_i32 s98, s30, -8
	v_mov_b32_e32 v30, s98
	ds_read_b32 v247, v30
	s_waitcnt lgkmcnt(0)
	v_readfirstlane_b32 s32, v239
	v_readfirstlane_b32 s99, v247
	ds_read_b32 v30, v30 offset:4
	s_ashr_i32 s98, s99, 5
	v_lshl_add_u32 v239, s98, 2, v195
	ds_read_b32 v247, v239 offset:256
	ds_read_b32 v239, v239
	s_waitcnt lgkmcnt(0)
	s_branch .LBB0_623

.LBB0_623:
	ds_read_b128 v[174:177], v212
	ds_read_b128 v[240:243], v212 offset:64
	ds_read_b128 v[248:251], v212 offset:128
	ds_read_b128 v[252:255], v212 offset:192
	s_mov_b32 s2, s99
	v_readfirstlane_b32 s3, v30
	s_mov_b32 s99, s3
	s_add_i32 s0, s31, 1
	s_cmp_lt_i32 s0, s28
	s_cselect_b64 s[18:19], -1, 0
	s_cmp_ge_i32 s0, s28
	s_cselect_b64 s[16:17], -1, 0
	s_and_b64 vcc, exec, s[16:17]
	s_waitcnt vmcnt(0)
	v_mov_b32_e32 v100, 0
	v_mov_b32_e32 v101, 0
	v_mov_b32_e32 v102, 0
	v_mov_b32_e32 v103, 0
	v_mov_b32_e32 v104, 0
	v_mov_b32_e32 v105, 0
	v_mov_b32_e32 v106, 0
	v_mov_b32_e32 v107, 0
	v_mov_b32_e32 v108, 0
	v_mov_b32_e32 v109, 0
	v_mov_b32_e32 v110, 0
	v_mov_b32_e32 v111, 0
	v_mov_b32_e32 v112, 0
	v_mov_b32_e32 v113, 0
	v_mov_b32_e32 v114, 0
	v_mov_b32_e32 v115, 0
	s_cbranch_vccnz .LBB0_625
	s_mul_i32 s0, s3, 0x60000
	s_mul_hi_i32 s1, s3, 0x60000
	s_add_u32 s0, s12, s0
	s_addc_u32 s1, s13, s1
	s_lshl_b32 s8, s3, 6
	s_ashr_i32 s9, s8, 31
	v_lshl_add_u64 v[30:31], v[166:167], 1, s[0:1]
	v_lshl_add_u64 v[100:101], v[168:169], 1, s[0:1]
	s_lshl_b64 s[0:1], s[8:9], 1
	s_add_u32 s0, s14, s0
	s_addc_u32 s1, s15, s1
	global_load_dwordx4 v[104:107], v[30:31], off offset:2048
	global_load_dwordx4 v[108:111], v[100:101], off offset:2048
	v_lshl_add_u64 v[30:31], v[170:171], 1, s[0:1]
	v_lshl_add_u64 v[100:101], v[172:173], 1, s[0:1]
	global_load_dwordx4 v[112:115], v[30:31], off
	s_nop 0
	global_load_dwordx4 v[100:103], v[100:101], off
.LBB0_625:
	s_lshl_b32 s0, 1, s2
	v_and_b32_e32 v31, s0, v247
	v_and_b32_e32 v30, s0, v239
	v_or_b32_e32 v118, v30, v31
	v_cmp_ne_u32_e64 s[8:9], 0, v31
	v_cmp_ne_u32_e64 s[0:1], 0, v30
	v_cmp_ne_u32_e32 vcc, 0, v118
	s_cbranch_vccz .LBB0_677
	s_lshl_b32 s2, s2, 6
	v_cndmask_b32_e64 v30, 0, 1, s[8:9]
	v_cndmask_b32_e64 v31, 0, 1, s[0:1]
	s_sub_i32 s0, s29, s2
	v_lshlrev_b16_e32 v30, 8, v30
	s_cmpk_lt_i32 s0, 0x80
	v_or_b32_e32 v30, v31, v30
	s_cselect_b64 s[20:21], -1, 0
	s_cmpk_gt_i32 s0, 0x7f
	s_setprio 1
	s_waitcnt lgkmcnt(3)
	v_mfma_f32_16x16x32_bf16 v[132:135], v[174:177], v[0:3], 0
	v_mfma_f32_16x16x32_bf16 v[116:119], v[174:177], v[16:19], 0
	ds_read_b128 v[174:177], v212 offset:4352
	s_waitcnt lgkmcnt(3)
	v_mfma_f32_16x16x32_bf16 v[132:135], v[240:243], v[4:7], v[132:135]
	v_mfma_f32_16x16x32_bf16 v[116:119], v[240:243], v[20:23], v[116:119]
	ds_read_b128 v[240:243], v212 offset:4416
	s_waitcnt lgkmcnt(3)
	v_mfma_f32_16x16x32_bf16 v[132:135], v[248:251], v[8:11], v[132:135]
	v_mfma_f32_16x16x32_bf16 v[116:119], v[248:251], v[24:27], v[116:119]
	ds_read_b128 v[248:251], v212 offset:4480
	s_waitcnt lgkmcnt(3)
	v_mfma_f32_16x16x32_bf16 v[132:135], v[252:255], v[12:15], v[132:135]
	v_mfma_f32_16x16x32_bf16 v[116:119], v[252:255], v[32:35], v[116:119]
	ds_read_b128 v[252:255], v212 offset:4544
	s_waitcnt lgkmcnt(3)
	v_mfma_f32_16x16x32_bf16 v[136:139], v[174:177], v[0:3], 0
	v_mfma_f32_16x16x32_bf16 v[120:123], v[174:177], v[16:19], 0
	ds_read_b128 v[174:177], v212 offset:8704
	s_waitcnt lgkmcnt(3)
	v_mfma_f32_16x16x32_bf16 v[136:139], v[240:243], v[4:7], v[136:139]
	v_mfma_f32_16x16x32_bf16 v[120:123], v[240:243], v[20:23], v[120:123]
	ds_read_b128 v[240:243], v212 offset:8768
	s_waitcnt lgkmcnt(3)
	v_mfma_f32_16x16x32_bf16 v[136:139], v[248:251], v[8:11], v[136:139]
	v_mfma_f32_16x16x32_bf16 v[120:123], v[248:251], v[24:27], v[120:123]
	ds_read_b128 v[248:251], v212 offset:8832
	s_waitcnt lgkmcnt(3)
	v_mfma_f32_16x16x32_bf16 v[136:139], v[252:255], v[12:15], v[136:139]
	v_mfma_f32_16x16x32_bf16 v[120:123], v[252:255], v[32:35], v[120:123]
	ds_read_b128 v[252:255], v212 offset:8896
	s_waitcnt lgkmcnt(3)
	v_mfma_f32_16x16x32_bf16 v[140:143], v[174:177], v[0:3], 0
	v_mfma_f32_16x16x32_bf16 v[124:127], v[174:177], v[16:19], 0
	ds_read_b128 v[174:177], v212 offset:13056
	s_waitcnt lgkmcnt(3)
	v_mfma_f32_16x16x32_bf16 v[140:143], v[240:243], v[4:7], v[140:143]
	v_mfma_f32_16x16x32_bf16 v[124:127], v[240:243], v[20:23], v[124:127]
	ds_read_b128 v[240:243], v212 offset:13120
	s_waitcnt lgkmcnt(3)
	v_mfma_f32_16x16x32_bf16 v[140:143], v[248:251], v[8:11], v[140:143]
	v_mfma_f32_16x16x32_bf16 v[124:127], v[248:251], v[24:27], v[124:127]
	ds_read_b128 v[248:251], v212 offset:13184
	s_waitcnt lgkmcnt(3)
	v_mfma_f32_16x16x32_bf16 v[140:143], v[252:255], v[12:15], v[140:143]
	v_mfma_f32_16x16x32_bf16 v[124:127], v[252:255], v[32:35], v[124:127]
	ds_read_b128 v[252:255], v212 offset:13248
	s_waitcnt lgkmcnt(3)
	v_mfma_f32_16x16x32_bf16 v[144:147], v[174:177], v[0:3], 0
	v_mfma_f32_16x16x32_bf16 v[128:131], v[174:177], v[16:19], 0
	s_waitcnt lgkmcnt(2)
	v_mfma_f32_16x16x32_bf16 v[144:147], v[240:243], v[4:7], v[144:147]
	v_mfma_f32_16x16x32_bf16 v[128:131], v[240:243], v[20:23], v[128:131]
	s_waitcnt lgkmcnt(1)
	v_mfma_f32_16x16x32_bf16 v[144:147], v[248:251], v[8:11], v[144:147]
	v_mfma_f32_16x16x32_bf16 v[128:131], v[248:251], v[24:27], v[128:131]
	s_waitcnt lgkmcnt(0)
	v_mfma_f32_16x16x32_bf16 v[144:147], v[252:255], v[12:15], v[144:147]
	v_mfma_f32_16x16x32_bf16 v[128:131], v[252:255], v[32:35], v[128:131]
	s_setprio 0
	ds_read2_b64 v[240:243], v213 offset1:4
	v_add_u32_e32 v239, 0x800, v213
	ds_read2_b64 v[248:251], v239 offset0:32 offset1:36
	v_add_u32_e32 v247, 0x1000, v213
	ds_read2_b64 v[252:255], v247 offset0:64 offset1:68
	v_add_u32_e32 v237, s2, v209
	s_mov_b64 s[0:1], -1
	v_and_b32_e32 v238, 1, v30
	v_or_b32_e32 v236, 2, v237
	v_or_b32_e32 v220, 3, v237
	s_cbranch_scc1 .LBB0_628
	v_sub_u32_e32 v179, v160, v237
	v_med3_i32 v30, v179, 0, v207
	v_lshl_add_u32 v30, v30, 2, v151
	ds_read_b32 v30, v30 offset:9216
	v_cmp_lt_i32_e64 s[0:1], -1, v179
	v_cmp_eq_u32_e32 vcc, 1, v238
	s_and_b64 s[0:1], s[0:1], vcc
	v_xad_u32 v31, v237, -1, v160
	s_waitcnt lgkmcnt(0)
	v_add_f32_e32 v30, v132, v30
	v_cndmask_b32_e64 v30, v208, v30, s[0:1]
	v_cmp_lt_i32_e64 s[0:1], -1, v31
	v_med3_i32 v31, v31, 0, v207
	v_lshl_add_u32 v31, v31, 2, v151
	ds_read_b32 v31, v31 offset:9216
	s_and_b64 s[0:1], s[0:1], vcc
	v_sub_u32_e32 v174, v160, v236
	v_sub_u32_e32 v175, v160, v220
	v_subrev_u32_e32 v177, 17, v179
	s_waitcnt lgkmcnt(0)
	v_add_f32_e32 v31, v133, v31
	v_cndmask_b32_e64 v31, v208, v31, s[0:1]
	v_cmp_lt_i32_e64 s[0:1], -1, v174
	v_med3_i32 v174, v174, 0, v207
	v_lshl_add_u32 v174, v174, 2, v151
	ds_read_b32 v174, v174 offset:9216
	s_and_b64 s[0:1], s[0:1], vcc
	v_max3_f32 v176, v30, s82, v31
	v_subrev_u32_e32 v180, 18, v179
	v_subrev_u32_e32 v181, 19, v179
	s_waitcnt lgkmcnt(0)
	v_add_f32_e32 v174, v134, v174
	v_cndmask_b32_e64 v174, v208, v174, s[0:1]
	v_cmp_lt_i32_e64 s[0:1], -1, v175
	v_med3_i32 v175, v175, 0, v207
	v_lshl_add_u32 v175, v175, 2, v151
	ds_read_b32 v175, v175 offset:9216
	s_and_b64 s[0:1], s[0:1], vcc
	v_subrev_u32_e32 v182, 32, v179
	v_subrev_u32_e32 v183, 33, v179
	v_subrev_u32_e32 v184, 34, v179
	s_waitcnt lgkmcnt(0)
	v_add_f32_e32 v175, v135, v175
	v_cndmask_b32_e64 v175, v208, v175, s[0:1]
	v_max3_f32 v178, v176, v174, v175
	v_add_u32_e32 v176, -16, v179
	v_cmp_lt_i32_e64 s[0:1], -1, v176
	v_med3_i32 v176, v176, 0, v207
	v_lshl_add_u32 v176, v176, 2, v151
	ds_read_b32 v176, v176 offset:9216
	s_and_b64 s[0:1], s[0:1], vcc
	v_subrev_u32_e32 v185, 35, v179
	v_subrev_u32_e32 v186, 48, v179
	v_subrev_u32_e32 v187, 49, v179
	s_waitcnt lgkmcnt(0)
	v_add_f32_e32 v176, v136, v176
	v_cndmask_b32_e64 v176, v208, v176, s[0:1]
	v_cmp_lt_i32_e64 s[0:1], -1, v177
	v_med3_i32 v177, v177, 0, v207
	v_lshl_add_u32 v177, v177, 2, v151
	ds_read_b32 v177, v177 offset:9216
	s_and_b64 s[0:1], s[0:1], vcc
	s_waitcnt lgkmcnt(0)
	v_add_f32_e32 v177, v137, v177
	v_cndmask_b32_e64 v177, v208, v177, s[0:1]
	v_cmp_lt_i32_e64 s[0:1], -1, v180
	v_med3_i32 v180, v180, 0, v207
	v_lshl_add_u32 v180, v180, 2, v151
	ds_read_b32 v180, v180 offset:9216
	s_and_b64 s[0:1], s[0:1], vcc
	v_max3_f32 v178, v178, v176, v177
	s_waitcnt lgkmcnt(0)
	v_add_f32_e32 v180, v138, v180
	v_cndmask_b32_e64 v180, v208, v180, s[0:1]
	v_cmp_lt_i32_e64 s[0:1], -1, v181
	s_and_b64 s[10:11], s[0:1], vcc
	v_med3_i32 v181, v181, 0, v207
	v_cmp_lt_i32_e64 s[0:1], -1, v182
	v_med3_i32 v182, v182, 0, v207
	v_lshl_add_u32 v181, v181, 2, v151
	v_lshl_add_u32 v182, v182, 2, v151
	ds_read_b32 v181, v181 offset:9216
	ds_read_b32 v182, v182 offset:9216
	s_and_b64 s[0:1], s[0:1], vcc
	s_waitcnt lgkmcnt(1)
	v_add_f32_e32 v181, v139, v181
	s_waitcnt lgkmcnt(0)
	v_add_f32_e32 v182, v140, v182
	v_cndmask_b32_e64 v182, v208, v182, s[0:1]
	v_cmp_lt_i32_e64 s[0:1], -1, v183
	v_med3_i32 v183, v183, 0, v207
	v_lshl_add_u32 v183, v183, 2, v151
	ds_read_b32 v183, v183 offset:9216
	s_and_b64 s[0:1], s[0:1], vcc
	v_cndmask_b32_e64 v181, v208, v181, s[10:11]
	v_max3_f32 v178, v178, v180, v181
	s_waitcnt lgkmcnt(0)
	v_add_f32_e32 v183, v141, v183
	v_cndmask_b32_e64 v183, v208, v183, s[0:1]
	v_cmp_lt_i32_e64 s[0:1], -1, v184
	v_med3_i32 v184, v184, 0, v207
	v_lshl_add_u32 v184, v184, 2, v151
	ds_read_b32 v184, v184 offset:9216
	s_and_b64 s[0:1], s[0:1], vcc
	v_max3_f32 v178, v178, v182, v183
	s_waitcnt lgkmcnt(0)
	v_add_f32_e32 v184, v142, v184
	v_cndmask_b32_e64 v184, v208, v184, s[0:1]
	v_cmp_lt_i32_e64 s[0:1], -1, v185
	v_med3_i32 v185, v185, 0, v207
	v_lshl_add_u32 v185, v185, 2, v151
	ds_read_b32 v185, v185 offset:9216
	s_and_b64 s[0:1], s[0:1], vcc
	s_waitcnt lgkmcnt(0)
	v_add_f32_e32 v185, v143, v185
	v_cndmask_b32_e64 v185, v208, v185, s[0:1]
	v_cmp_lt_i32_e64 s[0:1], -1, v186
	v_med3_i32 v186, v186, 0, v207
	v_lshl_add_u32 v186, v186, 2, v151
	ds_read_b32 v186, v186 offset:9216
	s_and_b64 s[0:1], s[0:1], vcc
	v_max3_f32 v178, v178, v184, v185
	s_waitcnt lgkmcnt(0)
	v_add_f32_e32 v186, v144, v186
	v_cndmask_b32_e64 v186, v208, v186, s[0:1]
	v_cmp_lt_i32_e64 s[0:1], -1, v187
	v_med3_i32 v187, v187, 0, v207
	v_lshl_add_u32 v187, v187, 2, v151
	ds_read_b32 v187, v187 offset:9216
	s_and_b64 s[0:1], s[0:1], vcc
	s_waitcnt lgkmcnt(0)
	v_add_f32_e32 v187, v145, v187
	v_cndmask_b32_e64 v187, v208, v187, s[0:1]
	v_max3_f32 v219, v178, v186, v187
	v_subrev_u32_e32 v178, 50, v179
	v_cmp_lt_i32_e64 s[0:1], -1, v178
	v_med3_i32 v178, v178, 0, v207
	v_lshl_add_u32 v178, v178, 2, v151
	ds_read_b32 v178, v178 offset:9216
	s_and_b64 s[0:1], s[0:1], vcc
	v_subrev_u32_e32 v179, 51, v179
	s_waitcnt lgkmcnt(0)
	v_add_f32_e32 v178, v146, v178
	v_cndmask_b32_e64 v178, v208, v178, s[0:1]
	v_cmp_lt_i32_e64 s[0:1], -1, v179
	v_med3_i32 v179, v179, 0, v207
	v_lshl_add_u32 v179, v179, 2, v151
	ds_read_b32 v179, v179 offset:9216
	s_and_b64 vcc, s[0:1], vcc
	s_mov_b64 s[0:1], 0
	s_waitcnt lgkmcnt(0)
	v_add_f32_e32 v179, v147, v179
	v_cndmask_b32_e32 v179, v208, v179, vcc
	v_max3_f32 v219, v219, v178, v179

.LBB0_648:
	s_andn2_b64 vcc, exec, s[16:17]
	s_mov_b64 s[0:1], -1
	s_ashr_i32 s98, s99, 5
	v_lshl_add_u32 v239, s98, 2, v195
	ds_read_b32 v247, v239 offset:256
	ds_read_b32 v239, v239
	v_mov_b32_e32 v30, s30
	ds_read_b32 v30, v30
	s_waitcnt lgkmcnt(0)
	s_barrier
	s_cbranch_vccnz .LBB0_650
	s_add_i32 s2, s31, 2
	s_mov_b64 s[0:1], 0
.LBB0_650:
	s_andn2_b64 vcc, exec, s[0:1]
	s_cbranch_vccnz .LBB0_622
	ds_read_b128 v[174:177], v214 offset:11328
	ds_read_b128 v[240:243], v214 offset:11392
	ds_read_b128 v[248:251], v214 offset:11456
	ds_read_b128 v[252:255], v214 offset:11520
	s_mov_b32 s2, s99
	v_readfirstlane_b32 s3, v30
	s_mov_b32 s99, s3
	s_add_i32 s31, s31, 2
	s_cmp_lt_i32 s31, s28
	s_waitcnt vmcnt(0)
	v_mov_b32_e32 v100, 0
	s_cselect_b64 s[16:17], -1, 0
	s_cmp_ge_i32 s31, s28
	v_mov_b32_e32 v101, 0
	v_mov_b32_e32 v102, 0
	v_mov_b32_e32 v103, 0
	v_mov_b32_e32 v104, 0
	v_mov_b32_e32 v105, 0
	v_mov_b32_e32 v106, 0
	v_mov_b32_e32 v107, 0
	v_mov_b32_e32 v108, 0
	v_mov_b32_e32 v109, 0
	v_mov_b32_e32 v110, 0
	v_mov_b32_e32 v111, 0
	v_mov_b32_e32 v112, 0
	v_mov_b32_e32 v113, 0
	v_mov_b32_e32 v114, 0
	v_mov_b32_e32 v115, 0
	s_cbranch_scc1 .LBB0_653
	s_mul_i32 s0, s3, 0x60000
	s_mul_hi_i32 s1, s3, 0x60000
	s_add_u32 s0, s12, s0
	s_addc_u32 s1, s13, s1
	s_lshl_b32 s8, s3, 6
	s_ashr_i32 s9, s8, 31
	v_lshl_add_u64 v[30:31], v[166:167], 1, s[0:1]
	v_lshl_add_u64 v[100:101], v[168:169], 1, s[0:1]
	s_lshl_b64 s[0:1], s[8:9], 1
	s_add_u32 s0, s14, s0
	s_addc_u32 s1, s15, s1
	global_load_dwordx4 v[104:107], v[30:31], off offset:2048
	global_load_dwordx4 v[108:111], v[100:101], off offset:2048
	v_lshl_add_u64 v[30:31], v[170:171], 1, s[0:1]
	v_lshl_add_u64 v[100:101], v[172:173], 1, s[0:1]
	global_load_dwordx4 v[112:115], v[30:31], off
	s_nop 0
	global_load_dwordx4 v[100:103], v[100:101], off
.LBB0_653:
	s_lshl_b32 s0, 1, s2
	v_and_b32_e32 v31, s0, v247
	v_and_b32_e32 v30, s0, v239
	v_or_b32_e32 v118, v30, v31
	v_cmp_ne_u32_e64 s[8:9], 0, v31
	v_cmp_ne_u32_e64 s[0:1], 0, v30
	v_cmp_ne_u32_e32 vcc, 0, v118
	s_cbranch_vccz .LBB0_678
	s_lshl_b32 s2, s2, 6
	v_cndmask_b32_e64 v30, 0, 1, s[8:9]
	v_cndmask_b32_e64 v31, 0, 1, s[0:1]
	s_sub_i32 s0, s29, s2
	v_lshlrev_b16_e32 v30, 8, v30
	s_cmpk_lt_i32 s0, 0x80
	v_or_b32_e32 v30, v31, v30
	s_cselect_b64 s[18:19], -1, 0
	s_cmpk_gt_i32 s0, 0x7f
	s_setprio 1
	s_waitcnt lgkmcnt(3)
	v_mfma_f32_16x16x32_bf16 v[132:135], v[174:177], v[0:3], 0
	v_mfma_f32_16x16x32_bf16 v[116:119], v[174:177], v[16:19], 0
	ds_read_b128 v[174:177], v214 offset:15680
	s_waitcnt lgkmcnt(3)
	v_mfma_f32_16x16x32_bf16 v[132:135], v[240:243], v[4:7], v[132:135]
	v_mfma_f32_16x16x32_bf16 v[116:119], v[240:243], v[20:23], v[116:119]
	ds_read_b128 v[240:243], v214 offset:15744
	s_waitcnt lgkmcnt(3)
	v_mfma_f32_16x16x32_bf16 v[132:135], v[248:251], v[8:11], v[132:135]
	v_mfma_f32_16x16x32_bf16 v[116:119], v[248:251], v[24:27], v[116:119]
	ds_read_b128 v[248:251], v214 offset:15808
	s_waitcnt lgkmcnt(3)
	v_mfma_f32_16x16x32_bf16 v[132:135], v[252:255], v[12:15], v[132:135]
	v_mfma_f32_16x16x32_bf16 v[116:119], v[252:255], v[32:35], v[116:119]
	ds_read_b128 v[252:255], v214 offset:15872
	s_waitcnt lgkmcnt(3)
	v_mfma_f32_16x16x32_bf16 v[136:139], v[174:177], v[0:3], 0
	v_mfma_f32_16x16x32_bf16 v[120:123], v[174:177], v[16:19], 0
	ds_read_b128 v[174:177], v214 offset:20032
	s_waitcnt lgkmcnt(3)
	v_mfma_f32_16x16x32_bf16 v[136:139], v[240:243], v[4:7], v[136:139]
	v_mfma_f32_16x16x32_bf16 v[120:123], v[240:243], v[20:23], v[120:123]
	ds_read_b128 v[240:243], v214 offset:20096
	s_waitcnt lgkmcnt(3)
	v_mfma_f32_16x16x32_bf16 v[136:139], v[248:251], v[8:11], v[136:139]
	v_mfma_f32_16x16x32_bf16 v[120:123], v[248:251], v[24:27], v[120:123]
	ds_read_b128 v[248:251], v214 offset:20160
	s_waitcnt lgkmcnt(3)
	v_mfma_f32_16x16x32_bf16 v[136:139], v[252:255], v[12:15], v[136:139]
	v_mfma_f32_16x16x32_bf16 v[120:123], v[252:255], v[32:35], v[120:123]
	ds_read_b128 v[252:255], v214 offset:20224
	s_waitcnt lgkmcnt(3)
	v_mfma_f32_16x16x32_bf16 v[140:143], v[174:177], v[0:3], 0
	v_mfma_f32_16x16x32_bf16 v[124:127], v[174:177], v[16:19], 0
	ds_read_b128 v[174:177], v214 offset:24384
	s_waitcnt lgkmcnt(3)
	v_mfma_f32_16x16x32_bf16 v[140:143], v[240:243], v[4:7], v[140:143]
	v_mfma_f32_16x16x32_bf16 v[124:127], v[240:243], v[20:23], v[124:127]
	ds_read_b128 v[240:243], v214 offset:24448
	s_waitcnt lgkmcnt(3)
	v_mfma_f32_16x16x32_bf16 v[140:143], v[248:251], v[8:11], v[140:143]
	v_mfma_f32_16x16x32_bf16 v[124:127], v[248:251], v[24:27], v[124:127]
	ds_read_b128 v[248:251], v214 offset:24512
	s_waitcnt lgkmcnt(3)
	v_mfma_f32_16x16x32_bf16 v[140:143], v[252:255], v[12:15], v[140:143]
	v_mfma_f32_16x16x32_bf16 v[124:127], v[252:255], v[32:35], v[124:127]
	ds_read_b128 v[252:255], v214 offset:24576
	s_waitcnt lgkmcnt(3)
	v_mfma_f32_16x16x32_bf16 v[144:147], v[174:177], v[0:3], 0
	v_mfma_f32_16x16x32_bf16 v[128:131], v[174:177], v[16:19], 0
	s_waitcnt lgkmcnt(2)
	v_mfma_f32_16x16x32_bf16 v[144:147], v[240:243], v[4:7], v[144:147]
	v_mfma_f32_16x16x32_bf16 v[128:131], v[240:243], v[20:23], v[128:131]
	s_waitcnt lgkmcnt(1)
	v_mfma_f32_16x16x32_bf16 v[144:147], v[248:251], v[8:11], v[144:147]
	v_mfma_f32_16x16x32_bf16 v[128:131], v[248:251], v[24:27], v[128:131]
	s_waitcnt lgkmcnt(0)
	v_mfma_f32_16x16x32_bf16 v[144:147], v[252:255], v[12:15], v[144:147]
	v_mfma_f32_16x16x32_bf16 v[128:131], v[252:255], v[32:35], v[128:131]
	s_setprio 0
	v_add_u32_e32 v239, 0x7000, v215
	ds_read2_b64 v[240:243], v239 offset0:8 offset1:12
	v_add_u32_e32 v247, 0x7800, v215
	ds_read2_b64 v[248:251], v247 offset0:40 offset1:44
	v_add_u32_e32 v237, s2, v209
	s_mov_b64 s[0:1], -1
	v_and_b32_e32 v238, 1, v30
	v_or_b32_e32 v236, 2, v237
	v_or_b32_e32 v217, 3, v237
	s_cbranch_scc1 .LBB0_656
	v_sub_u32_e32 v179, v160, v237
	v_med3_i32 v30, v179, 0, v207
	v_lshl_add_u32 v30, v30, 2, v151
	ds_read_b32 v30, v30 offset:9216
	v_cmp_lt_i32_e64 s[0:1], -1, v179
	v_cmp_eq_u32_e32 vcc, 1, v238
	s_and_b64 s[0:1], s[0:1], vcc
	v_xad_u32 v31, v237, -1, v160
	s_waitcnt lgkmcnt(0)
	v_add_f32_e32 v30, v132, v30
	v_cndmask_b32_e64 v30, v208, v30, s[0:1]
	v_cmp_lt_i32_e64 s[0:1], -1, v31
	v_med3_i32 v31, v31, 0, v207
	v_lshl_add_u32 v31, v31, 2, v151
	ds_read_b32 v31, v31 offset:9216
	s_and_b64 s[0:1], s[0:1], vcc
	v_sub_u32_e32 v174, v160, v236
	v_sub_u32_e32 v175, v160, v217
	v_subrev_u32_e32 v177, 17, v179
	s_waitcnt lgkmcnt(0)
	v_add_f32_e32 v31, v133, v31
	v_cndmask_b32_e64 v31, v208, v31, s[0:1]
	v_cmp_lt_i32_e64 s[0:1], -1, v174
	v_med3_i32 v174, v174, 0, v207
	v_lshl_add_u32 v174, v174, 2, v151
	ds_read_b32 v174, v174 offset:9216
	s_and_b64 s[0:1], s[0:1], vcc
	v_max3_f32 v176, v30, s82, v31
	v_subrev_u32_e32 v180, 18, v179
	v_subrev_u32_e32 v181, 19, v179
	s_waitcnt lgkmcnt(0)
	v_add_f32_e32 v174, v134, v174
	v_cndmask_b32_e64 v174, v208, v174, s[0:1]
	v_cmp_lt_i32_e64 s[0:1], -1, v175
	v_med3_i32 v175, v175, 0, v207
	v_lshl_add_u32 v175, v175, 2, v151
	ds_read_b32 v175, v175 offset:9216
	s_and_b64 s[0:1], s[0:1], vcc
	v_subrev_u32_e32 v182, 32, v179
	v_subrev_u32_e32 v183, 33, v179
	v_subrev_u32_e32 v184, 34, v179
	s_waitcnt lgkmcnt(0)
	v_add_f32_e32 v175, v135, v175
	v_cndmask_b32_e64 v175, v208, v175, s[0:1]
	v_max3_f32 v178, v176, v174, v175
	v_add_u32_e32 v176, -16, v179
	v_cmp_lt_i32_e64 s[0:1], -1, v176
	v_med3_i32 v176, v176, 0, v207
	v_lshl_add_u32 v176, v176, 2, v151
	ds_read_b32 v176, v176 offset:9216
	s_and_b64 s[0:1], s[0:1], vcc
	v_subrev_u32_e32 v185, 35, v179
	v_subrev_u32_e32 v186, 48, v179
	v_subrev_u32_e32 v187, 49, v179
	s_waitcnt lgkmcnt(0)
	v_add_f32_e32 v176, v136, v176
	v_cndmask_b32_e64 v176, v208, v176, s[0:1]
	v_cmp_lt_i32_e64 s[0:1], -1, v177
	v_med3_i32 v177, v177, 0, v207
	v_lshl_add_u32 v177, v177, 2, v151
	ds_read_b32 v177, v177 offset:9216
	s_and_b64 s[0:1], s[0:1], vcc
	s_waitcnt lgkmcnt(0)
	v_add_f32_e32 v177, v137, v177
	v_cndmask_b32_e64 v177, v208, v177, s[0:1]
	v_cmp_lt_i32_e64 s[0:1], -1, v180
	v_med3_i32 v180, v180, 0, v207
	v_lshl_add_u32 v180, v180, 2, v151
	ds_read_b32 v180, v180 offset:9216
	s_and_b64 s[0:1], s[0:1], vcc
	v_max3_f32 v178, v178, v176, v177
	s_waitcnt lgkmcnt(0)
	v_add_f32_e32 v180, v138, v180
	v_cndmask_b32_e64 v180, v208, v180, s[0:1]
	v_cmp_lt_i32_e64 s[0:1], -1, v181
	s_and_b64 s[10:11], s[0:1], vcc
	v_med3_i32 v181, v181, 0, v207
	v_cmp_lt_i32_e64 s[0:1], -1, v182
	v_med3_i32 v182, v182, 0, v207
	v_lshl_add_u32 v181, v181, 2, v151
	v_lshl_add_u32 v182, v182, 2, v151
	ds_read_b32 v181, v181 offset:9216
	ds_read_b32 v182, v182 offset:9216
	s_and_b64 s[0:1], s[0:1], vcc
	s_waitcnt lgkmcnt(1)
	v_add_f32_e32 v181, v139, v181
	s_waitcnt lgkmcnt(0)
	v_add_f32_e32 v182, v140, v182
	v_cndmask_b32_e64 v182, v208, v182, s[0:1]
	v_cmp_lt_i32_e64 s[0:1], -1, v183
	v_med3_i32 v183, v183, 0, v207
	v_lshl_add_u32 v183, v183, 2, v151
	ds_read_b32 v183, v183 offset:9216
	s_and_b64 s[0:1], s[0:1], vcc
	v_cndmask_b32_e64 v181, v208, v181, s[10:11]
	v_max3_f32 v178, v178, v180, v181
	s_waitcnt lgkmcnt(0)
	v_add_f32_e32 v183, v141, v183
	v_cndmask_b32_e64 v183, v208, v183, s[0:1]
	v_cmp_lt_i32_e64 s[0:1], -1, v184
	v_med3_i32 v184, v184, 0, v207
	v_lshl_add_u32 v184, v184, 2, v151
	ds_read_b32 v184, v184 offset:9216
	s_and_b64 s[0:1], s[0:1], vcc
	v_max3_f32 v178, v178, v182, v183
	s_waitcnt lgkmcnt(0)
	v_add_f32_e32 v184, v142, v184
	v_cndmask_b32_e64 v184, v208, v184, s[0:1]
	v_cmp_lt_i32_e64 s[0:1], -1, v185
	v_med3_i32 v185, v185, 0, v207
	v_lshl_add_u32 v185, v185, 2, v151
	ds_read_b32 v185, v185 offset:9216
	s_and_b64 s[0:1], s[0:1], vcc
	s_waitcnt lgkmcnt(0)
	v_add_f32_e32 v185, v143, v185
	v_cndmask_b32_e64 v185, v208, v185, s[0:1]
	v_cmp_lt_i32_e64 s[0:1], -1, v186
	v_med3_i32 v186, v186, 0, v207
	v_lshl_add_u32 v186, v186, 2, v151
	ds_read_b32 v186, v186 offset:9216
	s_and_b64 s[0:1], s[0:1], vcc
	v_max3_f32 v178, v178, v184, v185
	s_waitcnt lgkmcnt(0)
	v_add_f32_e32 v186, v144, v186
	v_cndmask_b32_e64 v186, v208, v186, s[0:1]
	v_cmp_lt_i32_e64 s[0:1], -1, v187
	v_med3_i32 v187, v187, 0, v207
	v_lshl_add_u32 v187, v187, 2, v151
	ds_read_b32 v187, v187 offset:9216
	s_and_b64 s[0:1], s[0:1], vcc
	s_waitcnt lgkmcnt(0)
	v_add_f32_e32 v187, v145, v187
	v_cndmask_b32_e64 v187, v208, v187, s[0:1]
	v_max3_f32 v218, v178, v186, v187
	v_subrev_u32_e32 v178, 50, v179
	v_cmp_lt_i32_e64 s[0:1], -1, v178
	v_med3_i32 v178, v178, 0, v207
	v_lshl_add_u32 v178, v178, 2, v151
	ds_read_b32 v178, v178 offset:9216
	s_and_b64 s[0:1], s[0:1], vcc
	v_subrev_u32_e32 v179, 51, v179
	s_waitcnt lgkmcnt(0)
	v_add_f32_e32 v178, v146, v178
	v_cndmask_b32_e64 v178, v208, v178, s[0:1]
	v_cmp_lt_i32_e64 s[0:1], -1, v179
	v_med3_i32 v179, v179, 0, v207
	v_lshl_add_u32 v179, v179, 2, v151
	ds_read_b32 v179, v179 offset:9216
	s_and_b64 vcc, s[0:1], vcc
	s_mov_b64 s[0:1], 0
	s_waitcnt lgkmcnt(0)
	v_add_f32_e32 v179, v147, v179
	v_cndmask_b32_e32 v179, v208, v179, vcc
	v_max3_f32 v218, v218, v178, v179

.LBB0_676:
	s_ashr_i32 s98, s99, 5
	v_lshl_add_u32 v239, s98, 2, v195
	ds_read_b32 v247, v239 offset:256
	ds_read_b32 v239, v239
	v_mov_b32_e32 v30, s30
	ds_read_b32 v30, v30 offset:4
	s_waitcnt lgkmcnt(0)
	s_barrier
	s_add_i32 s30, s30, 8
	s_cmp_lt_i32 s31, s28
	s_cbranch_scc1 .LBB0_623
	s_branch .LBB0_681
